# nt hint on norm1 x loads and final-norm loads/stores (long-reuse-distance streams); on top of v23
# speedup vs baseline: 1.0009x; 1.0009x over previous
; __device__ __forceinline__ unsigned pk2(float lo, float hi) { return f2bf(lo) | (f2bf(hi) << 16); }
; __device__ __forceinline__ void norm_mod_phase(const float* x, const float* x0src, size_t x0stride, float* h0buf, const float* g, const float* sh, const float* sc, bf16* XN, int gw, int NGW, int lane) {
;     ...
;     for (int k = 0; k < rpw; k += 4) {
;         f32x4 v[4][4];
; #pragma unroll
;         for (int r = 0; r < 4; ++r) { const int t = wi + wpb * (k + r); const bool t0 = t == 0;
;             const f32x4* xr = (const f32x4*)(t0 ? x0src + (size_t)b * x0stride : x + ((size_t)b * T + t) * D) + lane;
; #pragma unroll
;             for (int j = 0; j < 4; ++j) v[r][j] = xr[64 * j]; }
;         __builtin_amdgcn_sched_barrier(0);
; #pragma unroll
;         for (int r = 0; r < 4; ++r) { const int t = wi + wpb * (k + r); const bool t0 = t == 0; const size_t row = (size_t)b * T + t;
;             float ss = 0.f;
; #pragma unroll
;             for (int j = 0; j < 4; ++j) ss += (v[r][j].x * v[r][j].x + v[r][j].y * v[r][j].y) + (v[r][j].z * v[r][j].z + v[r][j].w * v[r][j].w);
;             const float rstd = 1.f / sqrtf(wave_sum(ss) * (1.f / D) + EPS);
; #pragma unroll
;             for (int j = 0; j < 4; ++j) { const int col = 4 * lane + 256 * j;
;                 const f32x4 h = v[r][j] * rstd * gm[j] + s0[j];
;                 v2u o; o.x = pk2(h.x, h.y); o.y = pk2(h.z, h.w);
;                 *(v2u*)(XN + row * D + col) = o;
;                 if (t0) *(f32x4*)(h0buf + b * D + col) = h; } }
.LBB0_164:
	s_add_i32 s0, s9, s78
	s_ashr_i32 s1, s0, 31
	s_lshl_b64 s[4:5], s[0:1], 12
	s_add_u32 s6, s16, s4
	s_addc_u32 s7, s17, s5
	s_cmp_eq_u32 s0, 0
	s_cselect_b64 s[72:73], -1, 0
	s_and_b64 s[4:5], s[72:73], exec
	s_cselect_b32 s74, s18, s6
	s_cselect_b32 s75, s20, s7
	s_add_i32 s70, s9, s61
	s_ashr_i32 s71, s70, 31
	s_lshl_b64 s[4:5], s[70:71], 12
	s_add_u32 s6, s16, s4
	s_addc_u32 s7, s17, s5
	s_cmp_eq_u32 s70, 0
	s_cselect_b64 s[68:69], -1, 0
	s_and_b64 s[4:5], s[68:69], exec
	s_cselect_b32 s80, s18, s6
	s_cselect_b32 s81, s20, s7
	s_add_i32 s66, s9, s76
	s_ashr_i32 s67, s66, 31
	s_lshl_b64 s[4:5], s[66:67], 12
	s_add_u32 s6, s16, s4
	s_addc_u32 s7, s17, s5
	s_cmp_eq_u32 s66, 0
	s_cselect_b64 s[64:65], -1, 0
	s_and_b64 s[4:5], s[64:65], exec
	s_cselect_b32 s82, s18, s6
	s_cselect_b32 s83, s20, s7
	s_add_i32 s6, s9, s77
	s_ashr_i32 s7, s6, 31
	s_lshl_b64 s[4:5], s[6:7], 12
	s_add_u32 s19, s16, s4
	s_addc_u32 s79, s17, s5
	s_cmp_eq_u32 s6, 0
	s_cselect_b64 s[4:5], -1, 0
	s_and_b64 s[84:85], s[4:5], exec
	s_cselect_b32 s84, s18, s19
	s_cselect_b32 s85, s20, s79
	global_load_dwordx4 v[76:79], v110, s[74:75] nt
	global_load_dwordx4 v[72:75], v110, s[74:75] offset:1024 nt
	global_load_dwordx4 v[68:71], v110, s[74:75] offset:2048 nt
	global_load_dwordx4 v[64:67], v110, s[74:75] offset:3072 nt
	global_load_dwordx4 v[60:63], v110, s[80:81] nt
	global_load_dwordx4 v[56:59], v110, s[80:81] offset:1024 nt
	global_load_dwordx4 v[52:55], v110, s[80:81] offset:2048 nt
	global_load_dwordx4 v[48:51], v110, s[80:81] offset:3072 nt
	global_load_dwordx4 v[44:47], v110, s[82:83] nt
	global_load_dwordx4 v[40:43], v110, s[82:83] offset:1024 nt
	global_load_dwordx4 v[36:39], v110, s[82:83] offset:2048 nt
	global_load_dwordx4 v[32:35], v110, s[82:83] offset:3072 nt
	global_load_dwordx4 v[28:31], v110, s[84:85] nt
	global_load_dwordx4 v[24:27], v110, s[84:85] offset:1024 nt
	global_load_dwordx4 v[20:23], v110, s[84:85] offset:2048 nt
	global_load_dwordx4 v[16:19], v110, s[84:85] offset:3072 nt
	s_lshl_b64 s[74:75], s[0:1], 11
	s_cmp_lg_u32 s0, 0
	s_waitcnt vmcnt(15)
	v_pk_mul_f32 v[100:101], v[78:79], v[78:79]
	v_pk_mul_f32 v[102:103], v[76:77], v[76:77]
	s_waitcnt vmcnt(12)
	v_mul_f32_e32 v111, v64, v64
	v_pk_mov_b32 v[112:113], v[102:103], v[100:101] op_sel:[1,0]
	v_mov_b32_e32 v103, v101
	v_pk_add_f32 v[100:101], v[112:113], v[102:103]
	v_pk_mul_f32 v[102:103], v[74:75], v[74:75]
	v_pk_mul_f32 v[112:113], v[72:73], v[72:73]
	v_pk_add_f32 v[100:101], v[100:101], v[100:101] op_sel:[0,1] op_sel_hi:[1,0]
	v_pk_mov_b32 v[114:115], v[112:113], v[102:103] op_sel:[1,0]
	v_mov_b32_e32 v113, v103
	v_pk_add_f32 v[102:103], v[114:115], v[112:113]
	v_mul_f32_e32 v112, v65, v65
	v_pk_add_f32 v[102:103], v[102:103], v[102:103] op_sel:[0,1] op_sel_hi:[1,0]
	v_mov_b32_e32 v101, v111
	v_mov_b32_e32 v103, v112
	v_pk_add_f32 v[100:101], v[100:101], v[102:103]
	v_mul_f32_e32 v102, v69, v69
	v_mul_f32_e32 v113, v66, v66
	v_pk_fma_f32 v[102:103], v[68:69], v[68:69], v[102:103] op_sel_hi:[1,1,0]
	v_mul_f32_e32 v112, v71, v71
	v_mul_f32_e32 v114, v67, v67
	v_mov_b32_e32 v103, v113
	v_pk_fma_f32 v[112:113], v[70:71], v[70:71], v[112:113] op_sel_hi:[1,1,0]
	s_nop 0
	v_mov_b32_e32 v113, v114
	v_pk_add_f32 v[102:103], v[102:103], v[112:113]
	s_nop 0
	v_pk_add_f32 v[100:101], v[100:101], v[102:103]
	s_nop 0
	v_add_f32_e32 v100, v100, v101
	ds_bpermute_b32 v101, v104, v100
	s_waitcnt lgkmcnt(0)
	v_add_f32_e32 v100, v100, v101
	ds_bpermute_b32 v101, v105, v100
	s_waitcnt lgkmcnt(0)
	v_add_f32_e32 v100, v100, v101
	ds_bpermute_b32 v101, v106, v100
	s_waitcnt lgkmcnt(0)
	v_add_f32_e32 v100, v100, v101
	ds_bpermute_b32 v101, v107, v100
	s_waitcnt lgkmcnt(0)
	v_add_f32_e32 v100, v100, v101
	ds_bpermute_b32 v101, v108, v100
	s_waitcnt lgkmcnt(0)
	v_add_f32_e32 v100, v100, v101
	ds_bpermute_b32 v101, v109, v100
	s_waitcnt lgkmcnt(0)
	v_add_f32_e32 v100, v100, v101
	v_fmamk_f32 v100, v100, 0x3a800000, v161
	v_mul_f32_e32 v101, 0x4f800000, v100
	v_cmp_gt_f32_e32 vcc, s58, v100
	s_nop 1
	v_cndmask_b32_e32 v100, v100, v101, vcc
	v_sqrt_f32_e32 v101, v100
	s_nop 0
	v_add_u32_e32 v102, -1, v101
	v_add_u32_e32 v103, 1, v101
	v_fma_f32 v111, -v102, v101, v100
	v_fma_f32 v112, -v103, v101, v100
	v_cmp_ge_f32_e64 s[0:1], 0, v111
	s_nop 1
	v_cndmask_b32_e64 v101, v101, v102, s[0:1]
	v_cmp_lt_f32_e64 s[0:1], 0, v112
	s_nop 1
	v_cndmask_b32_e64 v101, v101, v103, s[0:1]
	v_mul_f32_e32 v102, 0x37800000, v101
	v_cndmask_b32_e32 v101, v101, v102, vcc
	v_cmp_class_f32_e32 vcc, v100, v177
	s_nop 1
	v_cndmask_b32_e32 v100, v101, v100, vcc
	v_div_scale_f32 v101, s[0:1], v100, v100, 1.0
	v_rcp_f32_e32 v102, v101
	v_div_scale_f32 v103, vcc, 1.0, v100, 1.0
	v_fma_f32 v111, -v101, v102, 1.0
	v_fmac_f32_e32 v102, v111, v102
	v_mul_f32_e32 v111, v103, v102
	v_fma_f32 v112, -v101, v111, v103
	v_fmac_f32_e32 v111, v112, v102
	v_fma_f32 v101, -v101, v111, v103
	v_div_fmas_f32 v101, v101, v102, v111
	v_div_fixup_f32 v100, v101, v100, 1.0
	v_pk_mul_f32 v[76:77], v[76:77], v[100:101] op_sel_hi:[1,0]
	v_pk_mul_f32 v[78:79], v[78:79], v[100:101] op_sel_hi:[1,0]
	v_pk_fma_f32 v[76:77], v[82:83], v[76:77], v[0:1]
	v_pk_fma_f32 v[78:79], v[80:81], v[78:79], v[2:3]
	v_bfe_u32 v101, v76, 16, 1
	v_add3_u32 v101, v76, v101, s59
	v_bfe_u32 v102, v77, 16, 1
	v_lshrrev_b32_e32 v101, 16, v101
	v_add3_u32 v102, v77, v102, s59
	v_and_or_b32 v112, v102, s60, v101
	v_bfe_u32 v101, v78, 16, 1
	v_add3_u32 v101, v78, v101, s59
	v_bfe_u32 v102, v79, 16, 1
	v_lshrrev_b32_e32 v101, 16, v101
	v_add3_u32 v102, v79, v102, s59
	v_and_or_b32 v113, v102, s60, v101
	v_lshl_add_u64 v[102:103], v[98:99], 0, s[74:75]
	global_store_dwordx2 v[102:103], v[112:113], off
	s_cbranch_scc1 .LBB0_166
	global_store_dwordx4 v[96:97], v[76:79], off

; __device__ __forceinline__ void final_norm_phase(float* x, const float* x0buf, const float* g, int gw, int NGW, int lane) {
;     ...
;     for (int row0 = gw; row0 < M; row0 += 4 * NGW) {
;         f32x4 v[4][4];
; #pragma unroll
;         for (int r = 0; r < 4; ++r) { const int row = row0 + r * NGW; const bool t0 = (row & 4095) == 0;
;             const f32x4* xs = t0 ? (const f32x4*)(x0buf + (size_t)(row >> 12) * D) + lane : (const f32x4*)(x + (size_t)row * D) + lane;
; #pragma unroll
;             for (int j = 0; j < 4; ++j) v[r][j] = xs[64 * j]; }
;         __builtin_amdgcn_sched_barrier(0);
; #pragma unroll
;         for (int r = 0; r < 4; ++r) { const int row = row0 + r * NGW; f32x4* xr = (f32x4*)(x + (size_t)row * D) + lane;
;             float ss = 0.f;
; #pragma unroll
;             for (int j = 0; j < 4; ++j) ss += (v[r][j].x * v[r][j].x + v[r][j].y * v[r][j].y) + (v[r][j].z * v[r][j].z + v[r][j].w * v[r][j].w);
;             const float rstd = 1.f / sqrtf(wave_sum(ss) * (1.f / D) + EPS);
; #pragma unroll
;             for (int j = 0; j < 4; ++j) xr[64 * j] = v[r][j] * rstd * gg[j]; }
.LBB0_1404:
	global_load_dwordx4 v[36:39], v[84:85], off nt
	global_load_dwordx4 v[28:31], v[84:85], off offset:1024 nt
	global_load_dwordx4 v[24:27], v[84:85], off offset:2048 nt
	global_load_dwordx4 v[16:19], v[84:85], off offset:3072 nt
	s_add_i32 s10, s6, s12
	s_add_i32 s10, s10, s12
	s_waitcnt vmcnt(0)
	v_pk_mul_f32 v[84:85], v[78:79], v[78:79]
	v_pk_mul_f32 v[94:95], v[76:77], v[76:77]
	s_ashr_i32 s9, s8, 31
	v_pk_mov_b32 v[96:97], v[94:95], v[84:85] op_sel:[1,0]
	v_mov_b32_e32 v95, v85
	v_pk_add_f32 v[84:85], v[96:97], v[94:95]
	v_pk_mul_f32 v[94:95], v[74:75], v[74:75]
	v_pk_mul_f32 v[96:97], v[72:73], v[72:73]
	v_pk_add_f32 v[84:85], v[84:85], v[84:85] op_sel:[0,1] op_sel_hi:[1,0]
	v_pk_mov_b32 v[98:99], v[96:97], v[94:95] op_sel:[1,0]
	v_mov_b32_e32 v97, v95
	v_pk_add_f32 v[94:95], v[98:99], v[96:97]
	v_mul_f32_e32 v96, v64, v64
	v_mul_f32_e32 v97, v65, v65
	v_pk_add_f32 v[94:95], v[94:95], v[94:95] op_sel:[0,1] op_sel_hi:[1,0]
	v_mov_b32_e32 v85, v96
	v_mov_b32_e32 v95, v97
	v_pk_add_f32 v[84:85], v[84:85], v[94:95]
	v_mul_f32_e32 v94, v69, v69
	v_mul_f32_e32 v96, v71, v71
	v_mul_f32_e32 v98, v66, v66
	v_mul_f32_e32 v99, v67, v67
	v_pk_fma_f32 v[94:95], v[68:69], v[68:69], v[94:95] op_sel_hi:[1,1,0]
	v_pk_fma_f32 v[96:97], v[70:71], v[70:71], v[96:97] op_sel_hi:[1,1,0]
	v_mov_b32_e32 v95, v98
	v_mov_b32_e32 v97, v99
	v_pk_add_f32 v[94:95], v[94:95], v[96:97]
	s_ashr_i32 s7, s6, 31
	v_pk_add_f32 v[84:85], v[84:85], v[94:95]
	s_ashr_i32 s5, s4, 31
	v_add_f32_e32 v84, v84, v85
	ds_bpermute_b32 v85, v86, v84
	s_waitcnt lgkmcnt(0)
	v_add_f32_e32 v84, v84, v85
	ds_bpermute_b32 v85, v87, v84
	s_waitcnt lgkmcnt(0)
	v_add_f32_e32 v84, v84, v85
	ds_bpermute_b32 v85, v88, v84
	s_waitcnt lgkmcnt(0)
	v_add_f32_e32 v84, v84, v85
	ds_bpermute_b32 v85, v89, v84
	s_waitcnt lgkmcnt(0)
	v_add_f32_e32 v84, v84, v85
	ds_bpermute_b32 v85, v90, v84
	s_waitcnt lgkmcnt(0)
	v_add_f32_e32 v84, v84, v85
	ds_bpermute_b32 v85, v91, v84
	s_waitcnt lgkmcnt(0)
	v_add_f32_e32 v84, v84, v85
	v_fmamk_f32 v84, v84, 0x3a800000, v92
	v_mul_f32_e32 v85, 0x4f800000, v84
	v_cmp_gt_f32_e32 vcc, s15, v84
	s_nop 1
	v_cndmask_b32_e32 v84, v84, v85, vcc
	v_sqrt_f32_e32 v85, v84
	s_nop 0
	v_add_u32_e32 v94, -1, v85
	v_add_u32_e32 v95, 1, v85
	v_fma_f32 v96, -v94, v85, v84
	v_fma_f32 v97, -v95, v85, v84
	v_cmp_ge_f32_e64 s[0:1], 0, v96
	s_nop 1
	v_cndmask_b32_e64 v85, v85, v94, s[0:1]
	v_cmp_lt_f32_e64 s[0:1], 0, v97
	v_pk_mul_f32 v[96:97], v[60:61], v[60:61]
	s_nop 0
	v_cndmask_b32_e64 v85, v85, v95, s[0:1]
	v_mul_f32_e32 v94, 0x37800000, v85
	v_cndmask_b32_e32 v85, v85, v94, vcc
	v_cmp_class_f32_e32 vcc, v84, v93
	s_nop 1
	v_cndmask_b32_e32 v102, v85, v84, vcc
	v_div_scale_f32 v103, s[0:1], v102, v102, 1.0
	v_rcp_f32_e32 v104, v103
	v_div_scale_f32 v105, vcc, 1.0, v102, 1.0
	s_lshl_b64 s[0:1], s[8:9], 12
	v_fma_f32 v94, -v103, v104, 1.0
	v_fmac_f32_e32 v104, v94, v104
	v_pk_mul_f32 v[94:95], v[62:63], v[62:63]
	v_lshl_add_u64 v[84:85], v[80:81], 0, s[0:1]
	v_pk_mov_b32 v[98:99], v[96:97], v[94:95] op_sel:[1,0]
	v_mov_b32_e32 v97, v95
	v_pk_add_f32 v[94:95], v[98:99], v[96:97]
	v_pk_mul_f32 v[96:97], v[58:59], v[58:59]
	v_pk_mul_f32 v[98:99], v[56:57], v[56:57]
	v_pk_add_f32 v[94:95], v[94:95], v[94:95] op_sel:[0,1] op_sel_hi:[1,0]
	v_pk_mov_b32 v[100:101], v[98:99], v[96:97] op_sel:[1,0]
	v_mov_b32_e32 v99, v97
	v_pk_add_f32 v[96:97], v[100:101], v[98:99]
	v_mul_f32_e32 v98, v48, v48
	v_mul_f32_e32 v99, v49, v49
	v_pk_add_f32 v[96:97], v[96:97], v[96:97] op_sel:[0,1] op_sel_hi:[1,0]
	v_mov_b32_e32 v95, v98
	v_mov_b32_e32 v97, v99
	v_pk_add_f32 v[94:95], v[94:95], v[96:97]
	v_mul_f32_e32 v96, v53, v53
	v_mul_f32_e32 v98, v55, v55
	v_mul_f32_e32 v100, v50, v50
	v_mul_f32_e32 v101, v51, v51
	v_pk_fma_f32 v[96:97], v[52:53], v[52:53], v[96:97] op_sel_hi:[1,1,0]
	v_pk_fma_f32 v[98:99], v[54:55], v[54:55], v[98:99] op_sel_hi:[1,1,0]
	v_mov_b32_e32 v97, v100
	v_mov_b32_e32 v99, v101
	v_pk_add_f32 v[96:97], v[96:97], v[98:99]
	s_add_i32 s8, s10, s12
	v_pk_add_f32 v[94:95], v[94:95], v[96:97]
	v_mul_f32_e32 v96, v105, v104
	v_add_f32_e32 v94, v94, v95
	ds_bpermute_b32 v95, v86, v94
	v_fma_f32 v97, -v103, v96, v105
	v_fmac_f32_e32 v96, v97, v104
	v_fma_f32 v97, -v103, v96, v105
	s_waitcnt lgkmcnt(0)
	v_add_f32_e32 v95, v94, v95
	ds_bpermute_b32 v98, v87, v95
	v_div_fmas_f32 v94, v97, v104, v96
	v_div_fixup_f32 v94, v94, v102, 1.0
	v_pk_mul_f32 v[76:77], v[76:77], v[94:95] op_sel_hi:[1,0]
	s_waitcnt lgkmcnt(0)
	v_add_f32_e32 v95, v95, v98
	ds_bpermute_b32 v96, v88, v95
	v_pk_mul_f32 v[78:79], v[78:79], v[94:95] op_sel_hi:[1,0]
	v_pk_mul_f32 v[76:77], v[0:1], v[76:77]
	v_pk_mul_f32 v[78:79], v[2:3], v[78:79]
	global_store_dwordx4 v[84:85], v[76:79], off nt
	v_pk_mul_f32 v[72:73], v[72:73], v[94:95] op_sel_hi:[1,0]
	v_pk_mul_f32 v[74:75], v[74:75], v[94:95] op_sel_hi:[1,0]
	s_waitcnt lgkmcnt(0)
	v_add_f32_e32 v76, v95, v96
	ds_bpermute_b32 v77, v89, v76
	v_pk_mul_f32 v[74:75], v[6:7], v[74:75]
	v_pk_mul_f32 v[72:73], v[4:5], v[72:73]
	global_store_dwordx4 v[84:85], v[72:75], off offset:1024 nt
	v_pk_mul_f32 v[68:69], v[68:69], v[94:95] op_sel_hi:[1,0]
	s_waitcnt lgkmcnt(0)
	v_add_f32_e32 v76, v76, v77
	ds_bpermute_b32 v77, v90, v76
	v_pk_mul_f32 v[70:71], v[70:71], v[94:95] op_sel_hi:[1,0]
	v_pk_mul_f32 v[68:69], v[8:9], v[68:69]
	v_pk_mul_f32 v[70:71], v[10:11], v[70:71]
	global_store_dwordx4 v[84:85], v[68:71], off offset:2048 nt
	s_waitcnt lgkmcnt(0)
	v_add_f32_e32 v72, v76, v77
	ds_bpermute_b32 v73, v91, v72
	v_pk_mul_f32 v[64:65], v[64:65], v[94:95] op_sel_hi:[1,0]
	v_pk_mul_f32 v[66:67], v[66:67], v[94:95] op_sel_hi:[1,0]
	v_pk_mul_f32 v[64:65], v[12:13], v[64:65]
	v_pk_mul_f32 v[66:67], v[14:15], v[66:67]
	s_waitcnt lgkmcnt(0)
; __device__ __forceinline__ void final_norm_phase(float* x, const float* x0buf, const float* g, int gw, int NGW, int lane) {
;     ...
;         for (int r = 0; r < 4; ++r) { const int row = row0 + r * NGW; f32x4* xr = (f32x4*)(x + (size_t)row * D) + lane;
;             float ss = 0.f;
; #pragma unroll
;             for (int j = 0; j < 4; ++j) ss += (v[r][j].x * v[r][j].x + v[r][j].y * v[r][j].y) + (v[r][j].z * v[r][j].z + v[r][j].w * v[r][j].w);
;             const float rstd = 1.f / sqrtf(wave_sum(ss) * (1.f / D) + EPS);
; #pragma unroll
;             for (int j = 0; j < 4; ++j) xr[64 * j] = v[r][j] * rstd * gg[j]; }
	v_add_f32_e32 v68, v72, v73
	v_fmamk_f32 v68, v68, 0x3a800000, v92
	v_mul_f32_e32 v69, 0x4f800000, v68
	v_cmp_gt_f32_e32 vcc, s15, v68
	global_store_dwordx4 v[84:85], v[64:67], off offset:3072 nt
	s_nop 0
	v_cndmask_b32_e32 v68, v68, v69, vcc
	v_sqrt_f32_e32 v69, v68
	s_nop 0
	v_add_u32_e32 v64, -1, v69
	v_fma_f32 v65, -v64, v69, v68
	v_cmp_ge_f32_e64 s[0:1], 0, v65
	v_add_u32_e32 v65, 1, v69
	v_fma_f32 v66, -v65, v69, v68
	v_cndmask_b32_e64 v64, v69, v64, s[0:1]
	v_cmp_lt_f32_e64 s[0:1], 0, v66
	s_nop 1
	v_cndmask_b32_e64 v64, v64, v65, s[0:1]
	v_mul_f32_e32 v65, 0x37800000, v64
	v_cndmask_b32_e32 v64, v64, v65, vcc
	v_cmp_class_f32_e32 vcc, v68, v93
	s_nop 1
	v_cndmask_b32_e32 v74, v64, v68, vcc
	v_div_scale_f32 v75, s[0:1], v74, v74, 1.0
	v_rcp_f32_e32 v76, v75
	v_pk_mul_f32 v[68:69], v[44:45], v[44:45]
	v_div_scale_f32 v77, vcc, 1.0, v74, 1.0
	v_fma_f32 v66, -v75, v76, 1.0
	v_fmac_f32_e32 v76, v66, v76
	v_pk_mul_f32 v[66:67], v[46:47], v[46:47]
	s_lshl_b64 s[0:1], s[6:7], 12
	v_pk_mov_b32 v[70:71], v[68:69], v[66:67] op_sel:[1,0]
	v_mov_b32_e32 v69, v67
	v_pk_add_f32 v[66:67], v[70:71], v[68:69]
	v_pk_mul_f32 v[68:69], v[42:43], v[42:43]
	v_pk_mul_f32 v[70:71], v[40:41], v[40:41]
	v_pk_add_f32 v[66:67], v[66:67], v[66:67] op_sel:[0,1] op_sel_hi:[1,0]
	v_pk_mov_b32 v[72:73], v[70:71], v[68:69] op_sel:[1,0]
	v_mov_b32_e32 v71, v69
	v_pk_add_f32 v[68:69], v[72:73], v[70:71]
	v_mul_f32_e32 v70, v20, v20
	v_mul_f32_e32 v71, v21, v21
	v_pk_add_f32 v[68:69], v[68:69], v[68:69] op_sel:[0,1] op_sel_hi:[1,0]
	v_mov_b32_e32 v67, v70
	v_mov_b32_e32 v69, v71
	v_pk_add_f32 v[66:67], v[66:67], v[68:69]
	v_mul_f32_e32 v68, v33, v33
	v_mul_f32_e32 v70, v35, v35
	v_mul_f32_e32 v72, v22, v22
	v_mul_f32_e32 v73, v23, v23
	v_pk_fma_f32 v[68:69], v[32:33], v[32:33], v[68:69] op_sel_hi:[1,1,0]
	v_pk_fma_f32 v[70:71], v[34:35], v[34:35], v[70:71] op_sel_hi:[1,1,0]
	v_mov_b32_e32 v69, v72
	v_mov_b32_e32 v71, v73
	v_pk_add_f32 v[68:69], v[68:69], v[70:71]
	v_lshl_add_u64 v[64:65], v[80:81], 0, s[0:1]
	v_pk_add_f32 v[66:67], v[66:67], v[68:69]
	v_mul_f32_e32 v68, v77, v76
	v_add_f32_e32 v66, v66, v67
	ds_bpermute_b32 v67, v86, v66
	v_fma_f32 v69, -v75, v68, v77
	v_fmac_f32_e32 v68, v69, v76
	v_fma_f32 v69, -v75, v68, v77
	s_waitcnt lgkmcnt(0)
	v_add_f32_e32 v67, v66, v67
	ds_bpermute_b32 v70, v87, v67
	v_div_fmas_f32 v66, v69, v76, v68
	v_div_fixup_f32 v66, v66, v74, 1.0
	v_pk_mul_f32 v[60:61], v[60:61], v[66:67] op_sel_hi:[1,0]
	s_waitcnt lgkmcnt(0)
	v_add_f32_e32 v67, v67, v70
	ds_bpermute_b32 v68, v88, v67
	v_pk_mul_f32 v[62:63], v[62:63], v[66:67] op_sel_hi:[1,0]
	v_pk_mul_f32 v[60:61], v[0:1], v[60:61]
	v_pk_mul_f32 v[62:63], v[2:3], v[62:63]
	global_store_dwordx4 v[64:65], v[60:63], off nt
	v_pk_mul_f32 v[56:57], v[56:57], v[66:67] op_sel_hi:[1,0]
	v_pk_mul_f32 v[58:59], v[58:59], v[66:67] op_sel_hi:[1,0]
	s_waitcnt lgkmcnt(0)
	v_add_f32_e32 v60, v67, v68
	ds_bpermute_b32 v61, v89, v60
	v_pk_mul_f32 v[58:59], v[6:7], v[58:59]
	v_pk_mul_f32 v[56:57], v[4:5], v[56:57]
	global_store_dwordx4 v[64:65], v[56:59], off offset:1024 nt
	v_pk_mul_f32 v[52:53], v[52:53], v[66:67] op_sel_hi:[1,0]
	s_waitcnt lgkmcnt(0)
	v_add_f32_e32 v60, v60, v61
	ds_bpermute_b32 v61, v90, v60
	v_pk_mul_f32 v[54:55], v[54:55], v[66:67] op_sel_hi:[1,0]
	v_pk_mul_f32 v[52:53], v[8:9], v[52:53]
	v_pk_mul_f32 v[54:55], v[10:11], v[54:55]
	global_store_dwordx4 v[64:65], v[52:55], off offset:2048 nt
	s_waitcnt lgkmcnt(0)
	v_add_f32_e32 v56, v60, v61
	ds_bpermute_b32 v57, v91, v56
	v_pk_mul_f32 v[48:49], v[48:49], v[66:67] op_sel_hi:[1,0]
	v_pk_mul_f32 v[50:51], v[50:51], v[66:67] op_sel_hi:[1,0]
	v_pk_mul_f32 v[48:49], v[12:13], v[48:49]
	v_pk_mul_f32 v[50:51], v[14:15], v[50:51]
	s_waitcnt lgkmcnt(0)
	v_add_f32_e32 v52, v56, v57
	v_fmamk_f32 v52, v52, 0x3a800000, v92
	v_mul_f32_e32 v53, 0x4f800000, v52
	v_cmp_gt_f32_e32 vcc, s15, v52
	global_store_dwordx4 v[64:65], v[48:51], off offset:3072 nt
	s_nop 0
	v_cndmask_b32_e32 v52, v52, v53, vcc
	v_sqrt_f32_e32 v53, v52
	s_nop 0
	v_add_u32_e32 v48, -1, v53
	v_fma_f32 v49, -v48, v53, v52
	v_cmp_ge_f32_e64 s[0:1], 0, v49
	v_add_u32_e32 v49, 1, v53
	v_fma_f32 v50, -v49, v53, v52
	v_cndmask_b32_e64 v48, v53, v48, s[0:1]
	v_cmp_lt_f32_e64 s[0:1], 0, v50
	s_nop 1
	v_cndmask_b32_e64 v48, v48, v49, s[0:1]
	v_mul_f32_e32 v49, 0x37800000, v48
	v_cndmask_b32_e32 v48, v48, v49, vcc
	v_cmp_class_f32_e32 vcc, v52, v93
	s_nop 1
	v_cndmask_b32_e32 v58, v48, v52, vcc
	v_div_scale_f32 v59, s[0:1], v58, v58, 1.0
	v_rcp_f32_e32 v60, v59
	v_pk_mul_f32 v[52:53], v[36:37], v[36:37]
	s_lshl_b64 s[0:1], s[4:5], 12
	v_lshl_add_u64 v[48:49], v[80:81], 0, s[0:1]
	v_fma_f32 v50, -v59, v60, 1.0
	v_fmac_f32_e32 v60, v50, v60
	v_pk_mul_f32 v[50:51], v[38:39], v[38:39]
	s_cmp_lt_i32 s8, 0x8000
	v_pk_mov_b32 v[54:55], v[52:53], v[50:51] op_sel:[1,0]
	v_mov_b32_e32 v53, v51
	v_pk_add_f32 v[50:51], v[54:55], v[52:53]
	v_pk_mul_f32 v[52:53], v[30:31], v[30:31]
	v_pk_mul_f32 v[54:55], v[28:29], v[28:29]
	v_pk_add_f32 v[50:51], v[50:51], v[50:51] op_sel:[0,1] op_sel_hi:[1,0]
	v_pk_mov_b32 v[56:57], v[54:55], v[52:53] op_sel:[1,0]
	v_mov_b32_e32 v55, v53
	v_pk_add_f32 v[52:53], v[56:57], v[54:55]
	v_mul_f32_e32 v54, v16, v16
	v_mul_f32_e32 v55, v17, v17
	v_pk_add_f32 v[52:53], v[52:53], v[52:53] op_sel:[0,1] op_sel_hi:[1,0]
	v_mov_b32_e32 v51, v54
	v_mov_b32_e32 v53, v55
	v_pk_add_f32 v[50:51], v[50:51], v[52:53]
	v_mul_f32_e32 v52, v25, v25
	v_mul_f32_e32 v54, v27, v27
	v_mul_f32_e32 v56, v18, v18
	v_mul_f32_e32 v57, v19, v19
	v_pk_fma_f32 v[52:53], v[24:25], v[24:25], v[52:53] op_sel_hi:[1,1,0]
	v_pk_fma_f32 v[54:55], v[26:27], v[26:27], v[54:55] op_sel_hi:[1,1,0]
	v_mov_b32_e32 v53, v56
	v_mov_b32_e32 v55, v57
	v_pk_add_f32 v[52:53], v[52:53], v[54:55]
	s_nop 0
	v_pk_add_f32 v[50:51], v[50:51], v[52:53]
	v_div_scale_f32 v52, vcc, 1.0, v58, 1.0
	v_add_f32_e32 v50, v50, v51
	ds_bpermute_b32 v51, v86, v50
	v_mul_f32_e32 v53, v52, v60
	v_fma_f32 v54, -v59, v53, v52
	v_fmac_f32_e32 v53, v54, v60
	v_fma_f32 v52, -v59, v53, v52
	s_waitcnt lgkmcnt(0)
; __device__ __forceinline__ void final_norm_phase(float* x, const float* x0buf, const float* g, int gw, int NGW, int lane) {
;     ...
;     for (int row0 = gw; row0 < M; row0 += 4 * NGW) {
;         f32x4 v[4][4];
; #pragma unroll
;         for (int r = 0; r < 4; ++r) { const int row = row0 + r * NGW; const bool t0 = (row & 4095) == 0;
;             const f32x4* xs = t0 ? (const f32x4*)(x0buf + (size_t)(row >> 12) * D) + lane : (const f32x4*)(x + (size_t)row * D) + lane;
; #pragma unroll
;             for (int j = 0; j < 4; ++j) v[r][j] = xs[64 * j]; }
;         __builtin_amdgcn_sched_barrier(0);
; #pragma unroll
;         for (int r = 0; r < 4; ++r) { const int row = row0 + r * NGW; f32x4* xr = (f32x4*)(x + (size_t)row * D) + lane;
;             float ss = 0.f;
; #pragma unroll
;             for (int j = 0; j < 4; ++j) ss += (v[r][j].x * v[r][j].x + v[r][j].y * v[r][j].y) + (v[r][j].z * v[r][j].z + v[r][j].w * v[r][j].w);
;             const float rstd = 1.f / sqrtf(wave_sum(ss) * (1.f / D) + EPS);
; #pragma unroll
;             for (int j = 0; j < 4; ++j) xr[64 * j] = v[r][j] * rstd * gg[j]; }
	v_add_f32_e32 v50, v50, v51
	ds_bpermute_b32 v51, v87, v50
	v_div_fmas_f32 v52, v52, v60, v53
	s_waitcnt lgkmcnt(0)
	v_add_f32_e32 v51, v50, v51
	ds_bpermute_b32 v53, v88, v51
	v_div_fixup_f32 v50, v52, v58, 1.0
	v_pk_mul_f32 v[44:45], v[44:45], v[50:51] op_sel_hi:[1,0]
	v_pk_mul_f32 v[46:47], v[46:47], v[50:51] op_sel_hi:[1,0]
	v_pk_mul_f32 v[44:45], v[0:1], v[44:45]
	s_waitcnt lgkmcnt(0)
	v_add_f32_e32 v51, v51, v53
	ds_bpermute_b32 v52, v89, v51
	v_pk_mul_f32 v[46:47], v[2:3], v[46:47]
	global_store_dwordx4 v[48:49], v[44:47], off nt
	v_pk_mul_f32 v[40:41], v[40:41], v[50:51] op_sel_hi:[1,0]
	v_pk_mul_f32 v[42:43], v[42:43], v[50:51] op_sel_hi:[1,0]
	s_waitcnt lgkmcnt(0)
	v_add_f32_e32 v44, v51, v52
	ds_bpermute_b32 v45, v90, v44
	v_pk_mul_f32 v[42:43], v[6:7], v[42:43]
	v_pk_mul_f32 v[40:41], v[4:5], v[40:41]
	global_store_dwordx4 v[48:49], v[40:43], off offset:1024 nt
	v_pk_mul_f32 v[32:33], v[32:33], v[50:51] op_sel_hi:[1,0]
	v_pk_mul_f32 v[34:35], v[34:35], v[50:51] op_sel_hi:[1,0]
	s_waitcnt lgkmcnt(0)
	v_add_f32_e32 v40, v44, v45
	ds_bpermute_b32 v41, v91, v40
	v_pk_mul_f32 v[34:35], v[10:11], v[34:35]
	v_pk_mul_f32 v[32:33], v[8:9], v[32:33]
	global_store_dwordx4 v[48:49], v[32:35], off offset:2048 nt
	v_pk_mul_f32 v[20:21], v[20:21], v[50:51] op_sel_hi:[1,0]
	v_pk_mul_f32 v[22:23], v[22:23], v[50:51] op_sel_hi:[1,0]
	s_waitcnt lgkmcnt(0)
	v_add_f32_e32 v32, v40, v41
	v_fmamk_f32 v32, v32, 0x3a800000, v92
	v_mul_f32_e32 v33, 0x4f800000, v32
	v_cmp_gt_f32_e32 vcc, s15, v32
	v_pk_mul_f32 v[22:23], v[14:15], v[22:23]
	v_pk_mul_f32 v[20:21], v[12:13], v[20:21]
	v_cndmask_b32_e32 v32, v32, v33, vcc
	v_sqrt_f32_e32 v33, v32
	global_store_dwordx4 v[48:49], v[20:23], off offset:3072 nt
	v_add_u32_e32 v34, -1, v33
	v_fma_f32 v35, -v34, v33, v32
	v_cmp_ge_f32_e64 s[0:1], 0, v35
	v_add_u32_e32 v35, 1, v33
	s_nop 0
	v_cndmask_b32_e64 v34, v33, v34, s[0:1]
	v_fma_f32 v33, -v35, v33, v32
	v_cmp_lt_f32_e64 s[0:1], 0, v33
	s_nop 1
	v_cndmask_b32_e64 v33, v34, v35, s[0:1]
	v_mul_f32_e32 v34, 0x37800000, v33
	v_cndmask_b32_e32 v33, v33, v34, vcc
	v_cmp_class_f32_e32 vcc, v32, v93
	s_nop 1
	v_cndmask_b32_e32 v34, v33, v32, vcc
	v_div_scale_f32 v35, s[0:1], v34, v34, 1.0
	v_rcp_f32_e32 v40, v35
	v_lshl_add_u64 v[32:33], v[80:81], 0, s[2:3]
	v_fma_f32 v20, -v35, v40, 1.0
	v_fmac_f32_e32 v40, v20, v40
	v_div_scale_f32 v20, vcc, 1.0, v34, 1.0
	v_mul_f32_e32 v21, v20, v40
	v_fma_f32 v22, -v35, v21, v20
	v_fmac_f32_e32 v21, v22, v40
	v_fma_f32 v20, -v35, v21, v20
	v_div_fmas_f32 v20, v20, v40, v21
	v_div_fixup_f32 v34, v20, v34, 1.0
	v_pk_mul_f32 v[20:21], v[36:37], v[34:35] op_sel_hi:[1,0]
	v_pk_mul_f32 v[22:23], v[38:39], v[34:35] op_sel_hi:[1,0]
	v_pk_mul_f32 v[20:21], v[0:1], v[20:21]
	v_pk_mul_f32 v[22:23], v[2:3], v[22:23]
	global_store_dwordx4 v[32:33], v[20:23], off nt
	v_pk_mul_f32 v[16:17], v[16:17], v[34:35] op_sel_hi:[1,0]
	v_pk_mul_f32 v[18:19], v[18:19], v[34:35] op_sel_hi:[1,0]
	v_pk_mul_f32 v[20:21], v[28:29], v[34:35] op_sel_hi:[1,0]
	v_pk_mul_f32 v[22:23], v[30:31], v[34:35] op_sel_hi:[1,0]
	v_pk_mul_f32 v[20:21], v[4:5], v[20:21]
	v_pk_mul_f32 v[22:23], v[6:7], v[22:23]
	global_store_dwordx4 v[32:33], v[20:23], off offset:1024 nt
	v_pk_mul_f32 v[18:19], v[14:15], v[18:19]
	v_pk_mul_f32 v[16:17], v[12:13], v[16:17]
	v_pk_mul_f32 v[20:21], v[24:25], v[34:35] op_sel_hi:[1,0]
	v_pk_mul_f32 v[22:23], v[26:27], v[34:35] op_sel_hi:[1,0]
	v_pk_mul_f32 v[20:21], v[8:9], v[20:21]
	v_pk_mul_f32 v[22:23], v[10:11], v[22:23]
	global_store_dwordx4 v[32:33], v[20:23], off offset:2048 nt
	global_store_dwordx4 v[32:33], v[16:19], off offset:3072 nt
	s_cbranch_scc0 .LBB0_1408
.LBB0_1405:
	s_and_b32 s0, s8, 0xfff
	s_ashr_i32 s2, s8, 12
	s_cmp_eq_u32 s0, 0
	s_cselect_b64 vcc, -1, 0
	s_and_b64 s[0:1], vcc, exec
	s_cselect_b32 s0, s2, s8
	s_ashr_i32 s1, s0, 31
	v_cndmask_b32_e32 v17, v81, v83, vcc
	v_cndmask_b32_e32 v16, v80, v82, vcc
	s_lshl_b64 s[0:1], s[0:1], 12
	s_add_i32 s6, s8, s12
	v_lshl_add_u64 v[16:17], v[16:17], 0, s[0:1]
	s_and_b32 s0, s6, 0xfff
	s_ashr_i32 s2, s6, 12
	s_cmp_eq_u32 s0, 0
	s_cselect_b64 vcc, -1, 0
	s_and_b64 s[0:1], vcc, exec
	s_cselect_b32 s0, s2, s6
	s_ashr_i32 s1, s0, 31
	global_load_dwordx4 v[76:79], v[16:17], off nt
	global_load_dwordx4 v[72:75], v[16:17], off offset:1024 nt
	global_load_dwordx4 v[68:71], v[16:17], off offset:2048 nt
	global_load_dwordx4 v[64:67], v[16:17], off offset:3072 nt
	v_cndmask_b32_e32 v17, v81, v83, vcc
	v_cndmask_b32_e32 v16, v80, v82, vcc
	s_lshl_b64 s[0:1], s[0:1], 12
	s_add_i32 s4, s13, s8
	v_lshl_add_u64 v[16:17], v[16:17], 0, s[0:1]
	s_and_b32 s0, s4, 0xfff
	s_ashr_i32 s2, s4, 12
	s_cmp_eq_u32 s0, 0
	s_cselect_b64 vcc, -1, 0
	s_and_b64 s[0:1], vcc, exec
	s_cselect_b32 s0, s2, s4
	s_ashr_i32 s1, s0, 31
	global_load_dwordx4 v[60:63], v[16:17], off nt
	global_load_dwordx4 v[56:59], v[16:17], off offset:1024 nt
	global_load_dwordx4 v[52:55], v[16:17], off offset:2048 nt
	global_load_dwordx4 v[48:51], v[16:17], off offset:3072 nt
	v_cndmask_b32_e32 v17, v81, v83, vcc
	v_cndmask_b32_e32 v16, v80, v82, vcc
	s_lshl_b64 s[0:1], s[0:1], 12
	v_lshl_add_u64 v[16:17], v[16:17], 0, s[0:1]
	global_load_dwordx4 v[44:47], v[16:17], off nt
	global_load_dwordx4 v[40:43], v[16:17], off offset:1024 nt
	global_load_dwordx4 v[32:35], v[16:17], off offset:2048 nt
	global_load_dwordx4 v[20:23], v[16:17], off offset:3072 nt
	s_add_i32 s0, s14, s8
	s_and_b32 s1, s0, 0xfff
	s_cmp_eq_u32 s1, 0
	s_cbranch_scc1 .LBB0_1407
	s_ashr_i32 s1, s0, 31
	s_lshl_b64 s[2:3], s[0:1], 12
	v_lshl_add_u64 v[84:85], v[80:81], 0, s[2:3]
	s_cbranch_execnz .LBB0_1404
	s_branch .LBB0_1403
